# attention A: drop redundant vmcnt(0), K-fragment reads issued up front, compact v_max3 row-max tree + permlane32_swap cross-half max
# speedup vs baseline: 1.0093x; 1.0093x over previous
.LBB0_344:
	v_fma_f32 v0, v96, s43, -v151
	v_exp_f32_e32 v10, v0
	v_fma_f32 v0, v80, s43, -v151
	v_exp_f32_e32 v154, v0
	v_fma_f32 v0, v97, s43, -v151
	v_exp_f32_e32 v4, v0
	v_fma_f32 v0, v81, s43, -v151
	v_exp_f32_e32 v0, v0
	v_add_f32_e32 v5, v10, v154
	v_pk_add_f32 v[2:3], v[4:5], v[0:1]
	s_nop 0
	v_pk_add_f32 v[2:3], v[2:3], v[2:3] op_sel_hi:[0,1]
	v_fma_f32 v2, v98, s43, -v151
	v_exp_f32_e32 v5, v2
	v_fma_f32 v2, v82, s43, -v151
	v_exp_f32_e32 v155, v2
	v_fma_f32 v2, v99, s43, -v151
	v_exp_f32_e32 v6, v2
	v_fma_f32 v2, v83, s43, -v151
	v_exp_f32_e32 v2, v2
	v_add_f32_e32 v7, v5, v155
	v_cvt_pk_bf16_f32 v4, v10, v4
	v_cvt_pk_bf16_f32 v5, v5, v6
	v_pk_add_f32 v[8:9], v[6:7], v[2:3]
	v_fma_f32 v7, v84, s43, -v151
	v_fma_f32 v3, v100, s43, -v151
	v_exp_f32_e32 v156, v7
	v_fma_f32 v7, v101, s43, -v151
	v_pk_add_f32 v[152:153], v[8:9], v[8:9] op_sel_hi:[0,1]
	v_exp_f32_e32 v3, v3
	v_exp_f32_e32 v12, v7
	v_fma_f32 v7, v85, s43, -v151
	v_exp_f32_e32 v152, v7
	v_add3_u32 v7, s38, v185, v186
	v_add_f32_e32 v13, v3, v156
	v_add3_u32 v100, v7, v175, v176
	v_pk_add_f32 v[8:9], v[12:13], v[152:153]
	v_fma_f32 v7, v102, s43, -v151
	v_pk_add_f32 v[84:85], v[8:9], v[8:9] op_sel_hi:[0,1]
	v_exp_f32_e32 v153, v7
	v_fma_f32 v7, v103, s43, -v151
	v_add_u32_e32 v158, v100, v187
	v_fma_f32 v84, v86, s43, -v151
	v_exp_f32_e32 v86, v7
	ds_read_b64_tr_b16 v[8:9], v158 offset:8192
	ds_read_b64_tr_b16 v[10:11], v158 offset:10240
	v_add_u32_e32 v159, v100, v190
	v_fma_f32 v7, v104, s43, -v151
	v_cvt_pk_bf16_f32 v6, v3, v12
	ds_read_b64_tr_b16 v[12:13], v159 offset:8192
	ds_read_b64_tr_b16 v[14:15], v159 offset:10240
	ds_read_b64_tr_b16 v[80:81], v158 offset:12288
	ds_read_b64_tr_b16 v[82:83], v158 offset:14336
	v_exp_f32_e32 v157, v7
	v_fma_f32 v7, v105, s43, -v151
	v_exp_f32_e32 v104, v7
	v_cvt_pk_bf16_f32 v7, v153, v86
	v_add_u32_e32 v160, v100, v191
	v_add_u32_e32 v161, v100, v192
	s_waitcnt lgkmcnt(4)
	v_mfma_f32_32x32x16_bf16 v[64:79], v[8:11], v[4:7], v[64:79]
	ds_read_b64_tr_b16 v[8:9], v160 offset:8192
	ds_read_b64_tr_b16 v[10:11], v160 offset:10240
	ds_read_b64_tr_b16 v[96:97], v159 offset:12288
	ds_read_b64_tr_b16 v[98:99], v159 offset:14336
	v_fma_f32 v3, v106, s43, -v151
	v_fma_f32 v105, v110, s43, -v151
	v_exp_f32_e32 v3, v3
	v_exp_f32_e32 v163, v105
	s_waitcnt lgkmcnt(6)
	v_mfma_f32_32x32x16_bf16 v[48:63], v[12:15], v[4:7], v[48:63]
	v_fma_f32 v12, v107, s43, -v151
	v_exp_f32_e32 v106, v12
	ds_read_b64_tr_b16 v[12:13], v161 offset:8192
	ds_read_b64_tr_b16 v[14:15], v161 offset:10240
	ds_read_b64_tr_b16 v[100:101], v160 offset:12288
	ds_read_b64_tr_b16 v[102:103], v160 offset:14336
	s_waitcnt lgkmcnt(6)
	v_mfma_f32_32x32x16_bf16 v[32:47], v[8:11], v[4:7], v[32:47]
	v_fma_f32 v8, v108, s43, -v151
	v_exp_f32_e32 v162, v8
	v_fma_f32 v8, v109, s43, -v151
	v_exp_f32_e32 v108, v8
	ds_read_b64_tr_b16 v[8:9], v161 offset:12288
	ds_read_b64_tr_b16 v[10:11], v161 offset:14336
	s_waitcnt lgkmcnt(4)
	v_mfma_f32_32x32x16_bf16 v[16:31], v[12:15], v[4:7], v[16:31]
	v_fma_f32 v4, v111, s43, -v151
	v_exp_f32_e32 v110, v4
	v_cvt_pk_bf16_f32 v4, v157, v104
	v_cvt_pk_bf16_f32 v5, v3, v106
	v_cvt_pk_bf16_f32 v6, v162, v108
	v_cvt_pk_bf16_f32 v7, v163, v110
	v_fma_f32 v12, v87, s43, -v151
	s_nop 0
	v_mfma_f32_32x32x16_bf16 v[64:79], v[80:83], v[4:7], v[64:79]
	v_exp_f32_e32 v80, v84
	v_exp_f32_e32 v84, v12
	v_fma_f32 v81, v91, s43, -v151
	v_add_f32_e32 v87, v153, v80
	v_pk_add_f32 v[12:13], v[86:87], v[84:85]
	v_mfma_f32_32x32x16_bf16 v[48:63], v[96:99], v[4:7], v[48:63]
	v_add_f32_e64 v96, v12, v12
	v_add_f32_e64 v97, v12, v13
	v_fma_f32 v12, v88, s43, -v151
	v_exp_f32_e32 v111, v12
	v_fma_f32 v12, v89, s43, -v151
	v_exp_f32_e32 v96, v12
	v_add_f32_e32 v105, v157, v111
	s_waitcnt lgkmcnt(2)
	v_mfma_f32_32x32x16_bf16 v[32:47], v[100:103], v[4:7], v[32:47]
	v_add_f32_e64 v12, v104, v96
	v_add_f32_e64 v13, v105, v97
	v_add_f32_e64 v98, v12, v12
	v_add_f32_e64 v99, v12, v13
	v_fma_f32 v12, v90, s43, -v151
	v_exp_f32_e32 v97, v12
	ds_read_b64_tr_b16 v[12:13], v158 offset:16384
	ds_read_b64_tr_b16 v[14:15], v158 offset:18432
	v_exp_f32_e32 v98, v81
	s_waitcnt lgkmcnt(2)
	v_mfma_f32_32x32x16_bf16 v[16:31], v[8:11], v[4:7], v[16:31]
	v_cvt_pk_bf16_f32 v4, v154, v0
	v_cvt_pk_bf16_f32 v5, v155, v2
	v_cvt_pk_bf16_f32 v6, v156, v152
	v_cvt_pk_bf16_f32 v7, v80, v84
	ds_read_b64_tr_b16 v[8:9], v158 offset:20480
	ds_read_b64_tr_b16 v[10:11], v158 offset:22528
	v_add_f32_e32 v107, v3, v97
	v_pk_add_f32 v[2:3], v[106:107], v[98:99]
	s_waitcnt lgkmcnt(2)
	v_mfma_f32_32x32x16_bf16 v[64:79], v[12:15], v[4:7], v[64:79]
	ds_read_b64_tr_b16 v[12:13], v159 offset:16384
	ds_read_b64_tr_b16 v[14:15], v159 offset:18432
	ds_read_b64_tr_b16 v[80:81], v160 offset:16384
	ds_read_b64_tr_b16 v[82:83], v160 offset:18432
	ds_read_b64_tr_b16 v[84:85], v159 offset:20480
	ds_read_b64_tr_b16 v[86:87], v159 offset:22528
	v_fma_f32 v0, v92, s43, -v151
	v_pk_add_f32 v[100:101], v[2:3], v[2:3] op_sel_hi:[0,1]
	v_exp_f32_e32 v0, v0
	v_fma_f32 v2, v93, s43, -v151
	v_exp_f32_e32 v100, v2
	s_waitcnt lgkmcnt(4)
	v_mfma_f32_32x32x16_bf16 v[48:63], v[12:15], v[4:7], v[48:63]
	ds_read_b64_tr_b16 v[12:13], v160 offset:20480
	ds_read_b64_tr_b16 v[14:15], v160 offset:22528
	v_add_f32_e32 v109, v162, v0
	v_add_f32_e64 v2, v108, v100
	v_add_f32_e64 v3, v109, v101
	v_pk_add_f32 v[92:93], v[2:3], v[2:3] op_sel_hi:[0,1]
	v_fma_f32 v2, v94, s43, -v151
	v_cvt_pk_bf16_f32 v3, v97, v98
	s_waitcnt lgkmcnt(4)
	v_mfma_f32_32x32x16_bf16 v[32:47], v[80:83], v[4:7], v[32:47]
	ds_read_b64_tr_b16 v[80:81], v161 offset:16384
	ds_read_b64_tr_b16 v[82:83], v161 offset:18432
	ds_read_b64_tr_b16 v[88:89], v161 offset:20480
	ds_read_b64_tr_b16 v[90:91], v161 offset:22528
	s_waitcnt lgkmcnt(2)
	v_mfma_f32_32x32x16_bf16 v[16:31], v[80:83], v[4:7], v[16:31]
	v_exp_f32_e32 v6, v2
	v_fma_f32 v2, v95, s43, -v151
	v_exp_f32_e32 v92, v2
	v_cvt_pk_bf16_f32 v2, v111, v96
	v_cvt_pk_bf16_f32 v4, v0, v100
	v_add_f32_e32 v111, v163, v6
	v_cvt_pk_bf16_f32 v5, v6, v92
	v_pk_add_f32 v[6:7], v[110:111], v[92:93]
	s_nop 0
	v_mfma_f32_32x32x16_bf16 v[64:79], v[8:11], v[2:5], v[64:79]
	v_add_f32_e32 v0, v6, v7
	v_add_f32_e32 v150, v150, v0
	v_mfma_f32_32x32x16_bf16 v[48:63], v[84:87], v[2:5], v[48:63]
	v_mfma_f32_32x32x16_bf16 v[32:47], v[12:15], v[2:5], v[32:47]
	s_waitcnt lgkmcnt(0)
	v_mfma_f32_32x32x16_bf16 v[16:31], v[88:91], v[2:5], v[16:31]

.LBB0_355:
	s_cmp_gt_i32 s63, s52
	s_cbranch_scc1 .LBB0_345
	s_and_b32 s38, s63, 3
	s_mulk_i32 s38, 0x6000
	s_add_i32 s38, s38, 0
	v_add_u32_e32 v0, s38, v174
	v_add_u32_e32 v14, v0, v173
	v_add_u32_e32 v15, v0, v177
	ds_read_b128 v[2:5], v14
	ds_read_b128 v[6:9], v14 offset:4096
	ds_read_b128 v[10:13], v15
	ds_read_b128 v[152:155], v15 offset:4096
	v_add_u32_e32 v14, v0, v179
	v_add_u32_e32 v15, v0, v180
	ds_read_b128 v[156:159], v14
	ds_read_b128 v[160:163], v14 offset:4096
	ds_read_b128 v[244:247], v15
	ds_read_b128 v[248:251], v15 offset:4096
	s_waitcnt lgkmcnt(6)
	v_mfma_f32_32x32x16_bf16 v[96:111], v[2:5], v[112:115], 0
	v_mfma_f32_32x32x16_bf16 v[80:95], v[6:9], v[112:115], 0
	s_waitcnt lgkmcnt(4)
	v_mfma_f32_32x32x16_bf16 v[96:111], v[10:13], v[116:119], v[96:111]
	v_mfma_f32_32x32x16_bf16 v[80:95], v[152:155], v[116:119], v[80:95]
	s_waitcnt lgkmcnt(2)
	v_mfma_f32_32x32x16_bf16 v[96:111], v[156:159], v[120:123], v[96:111]
	v_mfma_f32_32x32x16_bf16 v[80:95], v[160:163], v[120:123], v[80:95]
	s_waitcnt lgkmcnt(0)
	v_mfma_f32_32x32x16_bf16 v[80:95], v[248:251], v[124:127], v[80:95]
	v_mfma_f32_32x32x16_bf16 v[96:111], v[244:247], v[124:127], v[96:111]
	s_nop 10
	v_max3_f32 v0, v80, v81, v82
	v_max3_f32 v2, v83, v84, v85
	v_max3_f32 v3, v86, v87, v88
	v_max3_f32 v4, v89, v90, v91
	v_max3_f32 v0, v0, v92, v93
	v_max3_f32 v2, v2, v94, v95
	v_max3_f32 v3, v3, v96, v97
	v_max3_f32 v4, v4, v98, v99
	v_max3_f32 v0, v0, v100, v101
	v_max3_f32 v2, v2, v102, v103
	v_max3_f32 v3, v3, v104, v105
	v_max3_f32 v4, v4, v106, v107
	v_max3_f32 v0, v0, v108, v109
	v_max3_f32 v2, v2, v110, v111
	v_max3_f32 v0, v0, v3, v4
	v_max_f32_e32 v0, v0, v2
	v_mul_f32_e32 v0, 0x3e38aa3b, v0
	v_mov_b32_e32 v2, v0
	v_mov_b32_e32 v3, v0
	s_nop 1
	v_permlane32_swap_b32_e32 v2, v3
	v_max_f32_e32 v0, v2, v3
	v_add_f32_e32 v2, 0x41000000, v151
	v_cmp_gt_f32_e32 vcc, v0, v2
	s_cbranch_vccz .LBB0_344
	v_max_f32_e32 v0, v0, v0
	v_max_f32_e32 v2, v151, v151
	v_max_f32_e32 v2, v2, v0
	v_sub_f32_e32 v0, v151, v2
	v_exp_f32_e32 v0, v0
	v_mov_b32_e32 v151, v2
	v_pk_mul_f32 v[78:79], v[0:1], v[78:79] op_sel_hi:[0,1]
	v_pk_mul_f32 v[76:77], v[0:1], v[76:77] op_sel_hi:[0,1]
	v_pk_mul_f32 v[74:75], v[0:1], v[74:75] op_sel_hi:[0,1]
	v_pk_mul_f32 v[72:73], v[0:1], v[72:73] op_sel_hi:[0,1]
	v_pk_mul_f32 v[70:71], v[0:1], v[70:71] op_sel_hi:[0,1]
	v_pk_mul_f32 v[68:69], v[0:1], v[68:69] op_sel_hi:[0,1]
	v_pk_mul_f32 v[66:67], v[0:1], v[66:67] op_sel_hi:[0,1]
	v_pk_mul_f32 v[64:65], v[0:1], v[64:65] op_sel_hi:[0,1]
	v_pk_mul_f32 v[62:63], v[0:1], v[62:63] op_sel_hi:[0,1]
	v_pk_mul_f32 v[60:61], v[0:1], v[60:61] op_sel_hi:[0,1]
	v_pk_mul_f32 v[58:59], v[0:1], v[58:59] op_sel_hi:[0,1]
	v_pk_mul_f32 v[56:57], v[0:1], v[56:57] op_sel_hi:[0,1]
	v_pk_mul_f32 v[54:55], v[0:1], v[54:55] op_sel_hi:[0,1]
	v_pk_mul_f32 v[52:53], v[0:1], v[52:53] op_sel_hi:[0,1]
	v_pk_mul_f32 v[50:51], v[0:1], v[50:51] op_sel_hi:[0,1]
	v_pk_mul_f32 v[48:49], v[0:1], v[48:49] op_sel_hi:[0,1]
	v_pk_mul_f32 v[46:47], v[0:1], v[46:47] op_sel_hi:[0,1]
	v_pk_mul_f32 v[44:45], v[0:1], v[44:45] op_sel_hi:[0,1]
	v_pk_mul_f32 v[42:43], v[0:1], v[42:43] op_sel_hi:[0,1]
	v_pk_mul_f32 v[40:41], v[0:1], v[40:41] op_sel_hi:[0,1]
	v_pk_mul_f32 v[38:39], v[0:1], v[38:39] op_sel_hi:[0,1]
	v_pk_mul_f32 v[36:37], v[0:1], v[36:37] op_sel_hi:[0,1]
	v_pk_mul_f32 v[34:35], v[0:1], v[34:35] op_sel_hi:[0,1]
	v_pk_mul_f32 v[32:33], v[0:1], v[32:33] op_sel_hi:[0,1]
	v_pk_mul_f32 v[30:31], v[0:1], v[30:31] op_sel_hi:[0,1]
	v_pk_mul_f32 v[28:29], v[0:1], v[28:29] op_sel_hi:[0,1]
	v_pk_mul_f32 v[26:27], v[0:1], v[26:27] op_sel_hi:[0,1]
	v_pk_mul_f32 v[24:25], v[0:1], v[24:25] op_sel_hi:[0,1]
	v_pk_mul_f32 v[22:23], v[0:1], v[22:23] op_sel_hi:[0,1]
	v_pk_mul_f32 v[20:21], v[0:1], v[20:21] op_sel_hi:[0,1]
	v_pk_mul_f32 v[18:19], v[0:1], v[18:19] op_sel_hi:[0,1]
	v_pk_mul_f32 v[16:17], v[0:1], v[16:17] op_sel_hi:[0,1]
	v_mul_f32_e32 v150, v150, v0
	s_branch .LBB0_344

.LBB0_362:
	v_fma_f32 v0, v96, s43, -v150
	v_exp_f32_e32 v10, v0
	v_fma_f32 v0, v80, s43, -v150
	v_exp_f32_e32 v151, v0
	v_fma_f32 v0, v97, s43, -v150
	v_exp_f32_e32 v4, v0
	v_fma_f32 v0, v81, s43, -v150
	v_exp_f32_e32 v0, v0
	v_add_f32_e32 v5, v10, v151
	v_pk_add_f32 v[2:3], v[4:5], v[0:1]
	s_nop 0
	v_pk_add_f32 v[2:3], v[2:3], v[2:3] op_sel_hi:[0,1]
	v_fma_f32 v2, v98, s43, -v150
	v_exp_f32_e32 v5, v2
	v_fma_f32 v2, v82, s43, -v150
	v_exp_f32_e32 v155, v2
	v_fma_f32 v2, v99, s43, -v150
	v_exp_f32_e32 v6, v2
	v_fma_f32 v2, v83, s43, -v150
	v_exp_f32_e32 v2, v2
	v_add_f32_e32 v7, v5, v155
	v_cvt_pk_bf16_f32 v4, v10, v4
	v_cvt_pk_bf16_f32 v5, v5, v6
	v_pk_add_f32 v[8:9], v[6:7], v[2:3]
	v_fma_f32 v7, v84, s43, -v150
	v_fma_f32 v3, v100, s43, -v150
	v_exp_f32_e32 v156, v7
	v_fma_f32 v7, v101, s43, -v150
	v_pk_add_f32 v[152:153], v[8:9], v[8:9] op_sel_hi:[0,1]
	v_exp_f32_e32 v3, v3
	v_exp_f32_e32 v12, v7
	v_fma_f32 v7, v85, s43, -v150
	v_exp_f32_e32 v152, v7
	v_add3_u32 v7, s28, v185, v186
	v_add_f32_e32 v13, v3, v156
	v_add3_u32 v100, v7, v175, v176
	v_pk_add_f32 v[8:9], v[12:13], v[152:153]
	v_fma_f32 v7, v102, s43, -v150
	v_pk_add_f32 v[84:85], v[8:9], v[8:9] op_sel_hi:[0,1]
	v_exp_f32_e32 v153, v7
	v_fma_f32 v7, v103, s43, -v150
	v_add_u32_e32 v158, v100, v187
	v_fma_f32 v84, v86, s43, -v150
	v_exp_f32_e32 v86, v7
	ds_read_b64_tr_b16 v[8:9], v158 offset:8192
	ds_read_b64_tr_b16 v[10:11], v158 offset:10240
	v_add_u32_e32 v159, v100, v190
	v_fma_f32 v7, v104, s43, -v150
	v_cvt_pk_bf16_f32 v6, v3, v12
	ds_read_b64_tr_b16 v[12:13], v159 offset:8192
	ds_read_b64_tr_b16 v[14:15], v159 offset:10240
	ds_read_b64_tr_b16 v[80:81], v158 offset:12288
	ds_read_b64_tr_b16 v[82:83], v158 offset:14336
	v_exp_f32_e32 v157, v7
	v_fma_f32 v7, v105, s43, -v150
	v_exp_f32_e32 v104, v7
	v_cvt_pk_bf16_f32 v7, v153, v86
	v_add_u32_e32 v160, v100, v191
	v_add_u32_e32 v161, v100, v192
	s_waitcnt lgkmcnt(4)
	v_mfma_f32_32x32x16_bf16 v[16:31], v[8:11], v[4:7], v[16:31]
	ds_read_b64_tr_b16 v[8:9], v160 offset:8192
	ds_read_b64_tr_b16 v[10:11], v160 offset:10240
	ds_read_b64_tr_b16 v[96:97], v159 offset:12288
	ds_read_b64_tr_b16 v[98:99], v159 offset:14336
	v_fma_f32 v3, v106, s43, -v150
	v_fma_f32 v105, v110, s43, -v150
	v_exp_f32_e32 v3, v3
	v_exp_f32_e32 v163, v105
	s_waitcnt lgkmcnt(6)
	v_mfma_f32_32x32x16_bf16 v[32:47], v[12:15], v[4:7], v[32:47]
	v_fma_f32 v12, v107, s43, -v150
	v_exp_f32_e32 v106, v12
	ds_read_b64_tr_b16 v[12:13], v161 offset:8192
	ds_read_b64_tr_b16 v[14:15], v161 offset:10240
	ds_read_b64_tr_b16 v[100:101], v160 offset:12288
	ds_read_b64_tr_b16 v[102:103], v160 offset:14336
	s_waitcnt lgkmcnt(6)
	v_mfma_f32_32x32x16_bf16 v[48:63], v[8:11], v[4:7], v[48:63]
	v_fma_f32 v8, v108, s43, -v150
	v_exp_f32_e32 v162, v8
	v_fma_f32 v8, v109, s43, -v150
	v_exp_f32_e32 v108, v8
	ds_read_b64_tr_b16 v[8:9], v161 offset:12288
	ds_read_b64_tr_b16 v[10:11], v161 offset:14336
	s_waitcnt lgkmcnt(4)
	v_mfma_f32_32x32x16_bf16 v[64:79], v[12:15], v[4:7], v[64:79]
	v_fma_f32 v4, v111, s43, -v150
	v_exp_f32_e32 v110, v4
	v_cvt_pk_bf16_f32 v4, v157, v104
	v_cvt_pk_bf16_f32 v5, v3, v106
	v_cvt_pk_bf16_f32 v6, v162, v108
	v_cvt_pk_bf16_f32 v7, v163, v110
	v_fma_f32 v12, v87, s43, -v150
	s_nop 0
	v_mfma_f32_32x32x16_bf16 v[16:31], v[80:83], v[4:7], v[16:31]
	v_exp_f32_e32 v80, v84
	v_exp_f32_e32 v84, v12
	v_fma_f32 v81, v91, s43, -v150
	v_add_f32_e32 v87, v153, v80
	v_pk_add_f32 v[12:13], v[86:87], v[84:85]
	v_mfma_f32_32x32x16_bf16 v[32:47], v[96:99], v[4:7], v[32:47]
	v_add_f32_e64 v96, v12, v12
	v_add_f32_e64 v97, v12, v13
	v_fma_f32 v12, v88, s43, -v150
	v_exp_f32_e32 v111, v12
	v_fma_f32 v12, v89, s43, -v150
	v_exp_f32_e32 v96, v12
	v_add_f32_e32 v105, v157, v111
	s_waitcnt lgkmcnt(2)
	v_mfma_f32_32x32x16_bf16 v[48:63], v[100:103], v[4:7], v[48:63]
	v_add_f32_e64 v12, v104, v96
	v_add_f32_e64 v13, v105, v97
	v_add_f32_e64 v98, v12, v12
	v_add_f32_e64 v99, v12, v13
	v_fma_f32 v12, v90, s43, -v150
	v_exp_f32_e32 v97, v12
	ds_read_b64_tr_b16 v[12:13], v158 offset:16384
	ds_read_b64_tr_b16 v[14:15], v158 offset:18432
	v_exp_f32_e32 v98, v81
	s_waitcnt lgkmcnt(2)
	v_mfma_f32_32x32x16_bf16 v[64:79], v[8:11], v[4:7], v[64:79]
	v_cvt_pk_bf16_f32 v4, v151, v0
	v_cvt_pk_bf16_f32 v5, v155, v2
	v_cvt_pk_bf16_f32 v6, v156, v152
	v_cvt_pk_bf16_f32 v7, v80, v84
	ds_read_b64_tr_b16 v[8:9], v158 offset:20480
	ds_read_b64_tr_b16 v[10:11], v158 offset:22528
	v_add_f32_e32 v107, v3, v97
	v_pk_add_f32 v[2:3], v[106:107], v[98:99]
	s_waitcnt lgkmcnt(2)
	v_mfma_f32_32x32x16_bf16 v[16:31], v[12:15], v[4:7], v[16:31]
	ds_read_b64_tr_b16 v[12:13], v159 offset:16384
	ds_read_b64_tr_b16 v[14:15], v159 offset:18432
	ds_read_b64_tr_b16 v[80:81], v160 offset:16384
	ds_read_b64_tr_b16 v[82:83], v160 offset:18432
	ds_read_b64_tr_b16 v[84:85], v159 offset:20480
	ds_read_b64_tr_b16 v[86:87], v159 offset:22528
	v_fma_f32 v0, v92, s43, -v150
	v_pk_add_f32 v[100:101], v[2:3], v[2:3] op_sel_hi:[0,1]
	v_exp_f32_e32 v0, v0
	v_fma_f32 v2, v93, s43, -v150
	v_exp_f32_e32 v100, v2
	s_waitcnt lgkmcnt(4)
	v_mfma_f32_32x32x16_bf16 v[32:47], v[12:15], v[4:7], v[32:47]
	ds_read_b64_tr_b16 v[12:13], v160 offset:20480
	ds_read_b64_tr_b16 v[14:15], v160 offset:22528
	v_add_f32_e32 v109, v162, v0
	v_add_f32_e64 v2, v108, v100
	v_add_f32_e64 v3, v109, v101
	v_pk_add_f32 v[92:93], v[2:3], v[2:3] op_sel_hi:[0,1]
	v_fma_f32 v2, v94, s43, -v150
	v_cvt_pk_bf16_f32 v3, v97, v98
	s_waitcnt lgkmcnt(4)
	v_mfma_f32_32x32x16_bf16 v[48:63], v[80:83], v[4:7], v[48:63]
	ds_read_b64_tr_b16 v[80:81], v161 offset:16384
	ds_read_b64_tr_b16 v[82:83], v161 offset:18432
	ds_read_b64_tr_b16 v[88:89], v161 offset:20480
	ds_read_b64_tr_b16 v[90:91], v161 offset:22528
	s_waitcnt lgkmcnt(2)
	v_mfma_f32_32x32x16_bf16 v[64:79], v[80:83], v[4:7], v[64:79]
	v_exp_f32_e32 v6, v2
	v_fma_f32 v2, v95, s43, -v150
	v_exp_f32_e32 v92, v2
	v_cvt_pk_bf16_f32 v2, v111, v96
	v_cvt_pk_bf16_f32 v4, v0, v100
	v_add_f32_e32 v111, v163, v6
	v_cvt_pk_bf16_f32 v5, v6, v92
	v_pk_add_f32 v[6:7], v[110:111], v[92:93]
	s_nop 0
	v_mfma_f32_32x32x16_bf16 v[16:31], v[8:11], v[2:5], v[16:31]
	v_add_f32_e32 v0, v6, v7
	v_add_f32_e32 v154, v154, v0
	v_mfma_f32_32x32x16_bf16 v[32:47], v[84:87], v[2:5], v[32:47]
	v_mfma_f32_32x32x16_bf16 v[48:63], v[12:15], v[2:5], v[48:63]
	s_waitcnt lgkmcnt(0)
	v_mfma_f32_32x32x16_bf16 v[64:79], v[88:91], v[2:5], v[64:79]

.LBB0_373:
	s_cmp_gt_i32 s34, s52
	s_cbranch_scc1 .LBB0_363
	s_and_b32 s28, s34, 3
	s_mulk_i32 s28, 0x6000
	s_add_i32 s28, s28, 0
	v_add_u32_e32 v0, s28, v174
	v_add_u32_e32 v14, v0, v173
	v_add_u32_e32 v15, v0, v177
	ds_read_b128 v[2:5], v14
	ds_read_b128 v[6:9], v14 offset:4096
	ds_read_b128 v[10:13], v15
	ds_read_b128 v[252:255], v15 offset:4096
	v_add_u32_e32 v14, v0, v179
	v_add_u32_e32 v15, v0, v180
	ds_read_b128 v[156:159], v14
	ds_read_b128 v[160:163], v14 offset:4096
	ds_read_b128 v[244:247], v15
	ds_read_b128 v[248:251], v15 offset:4096
	s_waitcnt lgkmcnt(6)
	v_mfma_f32_32x32x16_bf16 v[96:111], v[2:5], v[112:115], 0
	v_mfma_f32_32x32x16_bf16 v[80:95], v[6:9], v[112:115], 0
	s_waitcnt lgkmcnt(4)
	v_mfma_f32_32x32x16_bf16 v[96:111], v[10:13], v[116:119], v[96:111]
	v_mfma_f32_32x32x16_bf16 v[80:95], v[252:255], v[116:119], v[80:95]
	s_waitcnt lgkmcnt(2)
	v_mfma_f32_32x32x16_bf16 v[96:111], v[156:159], v[120:123], v[96:111]
	v_mfma_f32_32x32x16_bf16 v[80:95], v[160:163], v[120:123], v[80:95]
	s_waitcnt lgkmcnt(0)
	v_mfma_f32_32x32x16_bf16 v[80:95], v[248:251], v[124:127], v[80:95]
	v_mfma_f32_32x32x16_bf16 v[96:111], v[244:247], v[124:127], v[96:111]
	s_nop 10
	v_max3_f32 v0, v80, v81, v82
	v_max3_f32 v2, v83, v84, v85
	v_max3_f32 v3, v86, v87, v88
	v_max3_f32 v4, v89, v90, v91
	v_max3_f32 v0, v0, v92, v93
	v_max3_f32 v2, v2, v94, v95
	v_max3_f32 v3, v3, v96, v97
	v_max3_f32 v4, v4, v98, v99
	v_max3_f32 v0, v0, v100, v101
	v_max3_f32 v2, v2, v102, v103
	v_max3_f32 v3, v3, v104, v105
	v_max3_f32 v4, v4, v106, v107
	v_max3_f32 v0, v0, v108, v109
	v_max3_f32 v2, v2, v110, v111
	v_max3_f32 v0, v0, v3, v4
	v_max_f32_e32 v0, v0, v2
	v_mul_f32_e32 v0, 0x3e38aa3b, v0
	v_mov_b32_e32 v2, v0
	v_mov_b32_e32 v3, v0
	s_nop 1
	v_permlane32_swap_b32_e32 v2, v3
	v_max_f32_e32 v0, v2, v3
	v_add_f32_e32 v2, 0x41000000, v150
	v_cmp_gt_f32_e32 vcc, v0, v2
	s_cbranch_vccz .LBB0_362
	v_max_f32_e32 v0, v0, v0
	v_max_f32_e32 v2, v150, v150
	v_max_f32_e32 v2, v2, v0
	v_sub_f32_e32 v0, v150, v2
	v_exp_f32_e32 v0, v0
	v_mov_b32_e32 v150, v2
	v_pk_mul_f32 v[30:31], v[30:31], v[0:1] op_sel_hi:[1,0]
	v_pk_mul_f32 v[28:29], v[28:29], v[0:1] op_sel_hi:[1,0]
	v_pk_mul_f32 v[26:27], v[26:27], v[0:1] op_sel_hi:[1,0]
	v_pk_mul_f32 v[24:25], v[24:25], v[0:1] op_sel_hi:[1,0]
	v_pk_mul_f32 v[22:23], v[22:23], v[0:1] op_sel_hi:[1,0]
	v_pk_mul_f32 v[20:21], v[20:21], v[0:1] op_sel_hi:[1,0]
	v_pk_mul_f32 v[18:19], v[18:19], v[0:1] op_sel_hi:[1,0]
	v_pk_mul_f32 v[16:17], v[16:17], v[0:1] op_sel_hi:[1,0]
	v_pk_mul_f32 v[46:47], v[46:47], v[0:1] op_sel_hi:[1,0]
	v_pk_mul_f32 v[44:45], v[44:45], v[0:1] op_sel_hi:[1,0]
	v_pk_mul_f32 v[42:43], v[42:43], v[0:1] op_sel_hi:[1,0]
	v_pk_mul_f32 v[40:41], v[40:41], v[0:1] op_sel_hi:[1,0]
	v_pk_mul_f32 v[38:39], v[38:39], v[0:1] op_sel_hi:[1,0]
	v_pk_mul_f32 v[36:37], v[36:37], v[0:1] op_sel_hi:[1,0]
	v_pk_mul_f32 v[34:35], v[34:35], v[0:1] op_sel_hi:[1,0]
	v_pk_mul_f32 v[32:33], v[32:33], v[0:1] op_sel_hi:[1,0]
	v_pk_mul_f32 v[62:63], v[62:63], v[0:1] op_sel_hi:[1,0]
	v_pk_mul_f32 v[60:61], v[60:61], v[0:1] op_sel_hi:[1,0]
	v_pk_mul_f32 v[58:59], v[58:59], v[0:1] op_sel_hi:[1,0]
	v_pk_mul_f32 v[56:57], v[56:57], v[0:1] op_sel_hi:[1,0]
	v_pk_mul_f32 v[54:55], v[54:55], v[0:1] op_sel_hi:[1,0]
	v_pk_mul_f32 v[52:53], v[52:53], v[0:1] op_sel_hi:[1,0]
	v_pk_mul_f32 v[50:51], v[50:51], v[0:1] op_sel_hi:[1,0]
	v_pk_mul_f32 v[48:49], v[48:49], v[0:1] op_sel_hi:[1,0]
	v_pk_mul_f32 v[78:79], v[78:79], v[0:1] op_sel_hi:[1,0]
	v_pk_mul_f32 v[76:77], v[76:77], v[0:1] op_sel_hi:[1,0]
	v_pk_mul_f32 v[74:75], v[74:75], v[0:1] op_sel_hi:[1,0]
	v_pk_mul_f32 v[72:73], v[72:73], v[0:1] op_sel_hi:[1,0]
	v_pk_mul_f32 v[70:71], v[70:71], v[0:1] op_sel_hi:[1,0]
	v_pk_mul_f32 v[68:69], v[68:69], v[0:1] op_sel_hi:[1,0]
	v_pk_mul_f32 v[66:67], v[66:67], v[0:1] op_sel_hi:[1,0]
	v_pk_mul_f32 v[64:65], v[64:65], v[0:1] op_sel_hi:[1,0]
	v_mul_f32_e32 v154, v154, v0
	s_branch .LBB0_362

.LBB0_400:
	v_sub_f32_e32 v43, v122, v119
	v_sub_f32_e32 v34, v98, v119
	v_exp_f32_e32 v96, v43
	v_sub_f32_e32 v43, v121, v119
	v_exp_f32_e32 v34, v34
	v_exp_f32_e32 v44, v43
	v_sub_f32_e32 v43, v120, v119
	v_exp_f32_e32 v98, v43
	v_add_f32_e32 v45, v34, v96
	v_sub_f32_e32 v43, v95, v119
	v_sub_f32_e32 v42, v42, v119
	v_pk_add_f32 v[46:47], v[44:45], v[98:99]
	v_exp_f32_e32 v45, v43
	v_sub_f32_e32 v43, v94, v119
	v_exp_f32_e32 v94, v43
	v_sub_f32_e32 v43, v93, v119
	v_pk_add_f32 v[58:59], v[46:47], v[46:47] op_sel_hi:[0,1]
	v_exp_f32_e32 v56, v43
	v_sub_f32_e32 v43, v97, v119
	v_exp_f32_e32 v58, v43
	v_sub_f32_e32 v43, v92, v119
	v_add_f32_e32 v57, v45, v94
	v_exp_f32_e32 v50, v43
	v_sub_f32_e32 v43, v91, v119
	v_pk_add_f32 v[46:47], v[56:57], v[58:59]
	v_exp_f32_e32 v59, v43
	v_sub_f32_e32 v43, v90, v119
	v_pk_add_f32 v[60:61], v[46:47], v[46:47] op_sel_hi:[0,1]
	v_exp_f32_e32 v62, v43
	v_sub_f32_e32 v43, v86, v119
	v_exp_f32_e32 v60, v43
	v_sub_f32_e32 v43, v53, v119
	v_add_f32_e32 v63, v50, v59
	v_exp_f32_e32 v57, v43
	v_sub_f32_e32 v43, v52, v119
	v_pk_add_f32 v[46:47], v[62:63], v[60:61]
	v_exp_f32_e32 v61, v43
	v_sub_f32_e32 v43, v85, v119
	v_pk_add_f32 v[80:81], v[46:47], v[46:47] op_sel_hi:[0,1]
	v_exp_f32_e32 v52, v43
	v_sub_f32_e32 v43, v89, v119
	v_exp_f32_e32 v80, v43
	v_add_u32_e32 v43, s12, v106
	v_add3_u32 v63, v43, v175, v176
	v_add_f32_e32 v53, v57, v61
	v_sub_f32_e32 v43, v54, v119
	v_pk_add_f32 v[46:47], v[52:53], v[80:81]
	v_exp_f32_e32 v81, v43
	v_sub_f32_e32 v43, v55, v119
	v_exp_f32_e32 v92, v43
	v_sub_f32_e32 v43, v49, v119
	v_pk_add_f32 v[84:85], v[46:47], v[46:47] op_sel_hi:[0,1]
	v_exp_f32_e32 v86, v43
	v_sub_f32_e32 v43, v48, v119
	v_exp_f32_e32 v84, v43
	v_add_f32_e32 v87, v81, v92
	v_exp_f32_e32 v93, v42
	v_sub_f32_e32 v41, v41, v119
	v_pk_add_f32 v[42:43], v[86:87], v[84:85]
	v_exp_f32_e32 v95, v41
	v_pk_add_f32 v[88:89], v[42:43], v[42:43] op_sel_hi:[0,1]
	v_cvt_pk_bf16_f32 v42, v34, v44
	v_add_u32_e32 v34, v63, v107
	ds_read_b64_tr_b16 v[46:47], v34 offset:8192
	ds_read_b64_tr_b16 v[48:49], v34 offset:9216
	v_cvt_pk_bf16_f32 v43, v45, v56
	v_cvt_pk_bf16_f32 v44, v50, v62
	v_cvt_pk_bf16_f32 v45, v57, v52
	v_sub_f32_e32 v41, v51, v119
	v_sub_f32_e32 v37, v37, v119
	s_waitcnt lgkmcnt(0)
	v_mfma_f32_32x32x16_bf16 v[16:31], v[46:49], v[42:45], v[16:31]
	v_exp_f32_e32 v90, v41
	v_sub_f32_e32 v41, v83, v119
	v_add_u32_e32 v83, v63, v109
	v_exp_f32_e32 v62, v37
	v_sub_f32_e32 v37, v38, v119
	ds_read_b64_tr_b16 v[50:51], v83 offset:8192
	ds_read_b64_tr_b16 v[52:53], v83 offset:9216
	ds_read_b64_tr_b16 v[54:55], v34 offset:10240
	ds_read_b64_tr_b16 v[56:57], v34 offset:11264
	v_sub_f32_e32 v40, v40, v119
	v_exp_f32_e32 v85, v37
	v_sub_f32_e32 v37, v39, v119
	v_exp_f32_e32 v63, v40
	v_exp_f32_e32 v82, v37
	s_waitcnt lgkmcnt(2)
	v_mfma_f32_32x32x16_bf16 v[0:15], v[50:53], v[42:45], v[0:15]
	v_exp_f32_e32 v88, v41
	v_cvt_pk_bf16_f32 v38, v81, v86
	v_cvt_pk_bf16_f32 v39, v93, v90
	v_cvt_pk_bf16_f32 v40, v63, v62
	v_cvt_pk_bf16_f32 v41, v85, v82
	ds_read_b64_tr_b16 v[46:47], v83 offset:10240
	ds_read_b64_tr_b16 v[48:49], v83 offset:11264
	v_add_f32_e32 v91, v93, v95
	s_waitcnt lgkmcnt(2)
	v_mfma_f32_32x32x16_bf16 v[16:31], v[54:57], v[38:41], v[16:31]
	v_add_f32_e64 v42, v90, v88
	v_add_f32_e64 v43, v91, v89
	v_sub_f32_e32 v36, v36, v119
	v_add_f32_e64 v54, v42, v42
	v_add_f32_e64 v55, v42, v43
	ds_read_b64_tr_b16 v[42:43], v34 offset:12288
	ds_read_b64_tr_b16 v[44:45], v34 offset:13312
	v_exp_f32_e32 v56, v36
	v_cvt_pk_bf16_f32 v36, v96, v98
	v_cvt_pk_bf16_f32 v37, v94, v58
	s_waitcnt lgkmcnt(2)
	v_mfma_f32_32x32x16_bf16 v[0:15], v[46:49], v[38:41], v[0:15]
	v_cvt_pk_bf16_f32 v38, v59, v60
	v_cvt_pk_bf16_f32 v39, v61, v80
	ds_read_b64_tr_b16 v[46:47], v34 offset:14336
	ds_read_b64_tr_b16 v[48:49], v34 offset:15360
	v_sub_f32_e32 v33, v33, v119
	v_exp_f32_e32 v54, v33
	v_add_f32_e32 v63, v63, v56
	v_sub_f32_e32 v32, v32, v119
	s_waitcnt lgkmcnt(2)
	v_mfma_f32_32x32x16_bf16 v[16:31], v[42:45], v[36:39], v[16:31]
	ds_read_b64_tr_b16 v[40:41], v83 offset:12288
	ds_read_b64_tr_b16 v[42:43], v83 offset:13312
	v_add_f32_e64 v44, v62, v54
	v_add_f32_e64 v45, v63, v55
	ds_read_b64_tr_b16 v[50:51], v83 offset:14336
	ds_read_b64_tr_b16 v[52:53], v83 offset:15360
	v_pk_add_f32 v[44:45], v[44:45], v[44:45] op_sel_hi:[0,1]
	v_cvt_pk_bf16_f32 v33, v95, v88
	v_cvt_pk_bf16_f32 v34, v56, v54
	s_waitcnt lgkmcnt(2)
	v_mfma_f32_32x32x16_bf16 v[0:15], v[40:43], v[36:39], v[0:15]
	v_exp_f32_e32 v36, v32
	v_sub_f32_e32 v32, v35, v119
	v_exp_f32_e32 v44, v32
	v_cvt_pk_bf16_f32 v32, v92, v84
	v_add_f32_e32 v83, v85, v36
	v_cvt_pk_bf16_f32 v35, v36, v44
	v_pk_add_f32 v[36:37], v[82:83], v[44:45]
	s_nop 0
	v_mfma_f32_32x32x16_bf16 v[16:31], v[46:49], v[32:35], v[16:31]
	v_add_f32_e32 v36, v36, v37
	v_add_f32_e32 v101, v101, v36
	s_waitcnt lgkmcnt(0)
	v_mfma_f32_32x32x16_bf16 v[0:15], v[50:53], v[32:35], v[0:15]

	.amdhsa_kernel _Z6mk_fwd4Args
		.amdhsa_group_segment_fixed_size 0
		.amdhsa_private_segment_fixed_size 0
		.amdhsa_kernarg_size 456
		.amdhsa_user_sgpr_count 2
		.amdhsa_user_sgpr_dispatch_ptr 0
		.amdhsa_user_sgpr_queue_ptr 0
		.amdhsa_user_sgpr_kernarg_segment_ptr 1
		.amdhsa_user_sgpr_dispatch_id 0
		.amdhsa_user_sgpr_kernarg_preload_length 0
		.amdhsa_user_sgpr_kernarg_preload_offset 0
		.amdhsa_user_sgpr_private_segment_size 0
		.amdhsa_uses_dynamic_stack 0
		.amdhsa_enable_private_segment 0
		.amdhsa_system_sgpr_workgroup_id_x 1
		.amdhsa_system_sgpr_workgroup_id_y 0
		.amdhsa_system_sgpr_workgroup_id_z 0
		.amdhsa_system_sgpr_workgroup_info 0
		.amdhsa_system_vgpr_workitem_id 2
		.amdhsa_next_free_vgpr 256
		.amdhsa_next_free_sgpr 98
		.amdhsa_accum_offset 256
		.amdhsa_reserve_vcc 1
		.amdhsa_float_round_mode_32 0
		.amdhsa_float_round_mode_16_64 0
		.amdhsa_float_denorm_mode_32 3
		.amdhsa_float_denorm_mode_16_64 3
		.amdhsa_dx10_clamp 1
		.amdhsa_ieee_mode 1
		.amdhsa_fp16_overflow 0
		.amdhsa_tg_split 0
		.amdhsa_exception_fp_ieee_invalid_op 0
		.amdhsa_exception_fp_denorm_src 0
		.amdhsa_exception_fp_ieee_div_zero 0
		.amdhsa_exception_fp_ieee_overflow 0
		.amdhsa_exception_fp_ieee_underflow 0
		.amdhsa_exception_fp_ieee_inexact 0
		.amdhsa_exception_int_div_zero 0
	.end_amdhsa_kernel

amdhsa.kernels:
  - .agpr_count:     0
    .args:
      - .offset:         0
        .size:           200
        .value_kind:     by_value
      - .offset:         200
        .size:           4
        .value_kind:     hidden_block_count_x
      - .offset:         204
        .size:           4
        .value_kind:     hidden_block_count_y
      - .offset:         208
        .size:           4
        .value_kind:     hidden_block_count_z
      - .offset:         212
        .size:           2
        .value_kind:     hidden_group_size_x
      - .offset:         214
        .size:           2
        .value_kind:     hidden_group_size_y
      - .offset:         216
        .size:           2
        .value_kind:     hidden_group_size_z
      - .offset:         218
        .size:           2
        .value_kind:     hidden_remainder_x
      - .offset:         220
        .size:           2
        .value_kind:     hidden_remainder_y
      - .offset:         222
        .size:           2
        .value_kind:     hidden_remainder_z
      - .offset:         240
        .size:           8
        .value_kind:     hidden_global_offset_x
      - .offset:         248
        .size:           8
        .value_kind:     hidden_global_offset_y
      - .offset:         256
        .size:           8
        .value_kind:     hidden_global_offset_z
      - .offset:         264
        .size:           2
        .value_kind:     hidden_grid_dims
      - .offset:         288
        .size:           8
        .value_kind:     hidden_multigrid_sync_arg
      - .offset:         320
        .size:           4
        .value_kind:     hidden_dynamic_lds_size
    .group_segment_fixed_size: 0
    .kernarg_segment_align: 8
    .kernarg_segment_size: 456
    .language:       OpenCL C
    .language_version:
      - 2
      - 0
    .max_flat_workgroup_size: 512
    .name:           _Z6mk_fwd4Args
    .private_segment_fixed_size: 0
    .sgpr_count:     104
    .sgpr_spill_count: 69
    .symbol:         _Z6mk_fwd4Args.kd
    .uniform_work_group_size: 1
    .uses_dynamic_stack: false
    .vgpr_count:     256
    .vgpr_spill_count: 0
    .wavefront_size: 64
